# FNet stage-1 GEMM: workgroup index remapped so one XCD takes a 4x8 tile block (on top of per-XCD mixer queues)
# speedup vs baseline: 1.0059x; 1.0005x over previous
.LBB0_428:
	s_or_b64 exec, exec, s[6:7]
	s_mov_b32 s0, s93
	v_readlane_b32 s20, v253, 0
	v_mbcnt_lo_u32_b32 v0, -1, s0
	v_mbcnt_hi_u32_b32 v0, -1, v0
	v_or_b32_e32 v0, s84, v0
	s_mov_b32 s0, s88
	v_readlane_b32 s21, v253, 1
	s_mov_b64 s[0:1], s[20:21]
	v_readlane_b32 s4, v253, 54
	v_readlane_b32 s18, v254, 4
	v_readlane_b32 s19, v254, 5
	s_mov_b64 s[0:1], s[18:19]
	s_mov_b32 s0, s93
	v_readlane_b32 s5, v253, 55
	v_mbcnt_lo_u32_b32 v0, -1, s0
	v_mbcnt_hi_u32_b32 v0, -1, v0
	v_readlane_b32 s6, v253, 56
	v_readlane_b32 s7, v253, 57
	v_or_b32_e32 v0, s84, v0
	s_and_b32 s0, s88, 7
	s_lshl_b32 s0, s0, 5
	s_lshr_b32 s1, s88, 3
	s_or_b32 s0, s0, s1
	s_mov_b64 s[4:5], s[20:21]
	s_mov_b64 s[6:7], s[18:19]
	s_mov_b32 s1, s93
	v_readlane_b32 s10, v253, 60
	v_mbcnt_lo_u32_b32 v0, -1, s1
	v_mbcnt_hi_u32_b32 v0, -1, v0
	v_or_b32_e32 v8, s84, v0
	s_cmpk_lt_i32 s0, 0x300
	v_readfirstlane_b32 s10, v8
	v_readlane_b32 s8, v253, 58
	v_readlane_b32 s9, v253, 59
	v_readlane_b32 s11, v253, 61
	v_readlane_b32 s12, v253, 62
	v_readlane_b32 s13, v253, 63
	v_readlane_b32 s14, v254, 0
	v_readlane_b32 s15, v254, 1
	v_readlane_b32 s16, v254, 2
	v_readlane_b32 s17, v254, 3
	s_cbranch_scc0 .LBB0_448
	v_lshlrev_b32_e32 v0, 4, v8
	v_add_u32_e32 v1, 0x2000, v0
	v_ashrrev_i32_e32 v2, 31, v1
	v_lshrrev_b32_e32 v2, 22, v2
	v_add_u32_e32 v2, v1, v2
	v_ashrrev_i32_e32 v9, 10, v2
	v_mul_i32_i24_e32 v2, 0x400, v9
	v_sub_u32_e32 v1, v1, v2
	v_lshrrev_b32_e32 v2, 4, v1
	v_bitop3_b32 v1, v2, v1, 32 bitop3:0x6c
	v_ashrrev_i32_e32 v2, 31, v1
	v_lshrrev_b32_e32 v2, 26, v2
	v_add_u32_e32 v2, v1, v2
	v_lshlrev_b32_e32 v3, 3, v9
	v_ashrrev_i32_e32 v10, 6, v2
	v_and_b32_e32 v3, -16, v3
	v_add_u32_e32 v3, v10, v3
	v_and_b32_e32 v4, 3, v10
	s_mov_b32 s2, 0x3fffe0
	v_lshrrev_b32_e32 v5, 2, v3
	v_lshlrev_b32_e32 v6, 1, v3
	v_and_or_b32 v4, v3, s2, v4
	v_and_b32_e32 v5, 4, v5
	v_and_b32_e32 v6, 24, v6
	v_and_b32_e32 v2, 0xc0, v2
	v_or3_b32 v4, v4, v5, v6
	v_sub_u32_e32 v1, v1, v2
	v_mov_b32_e32 v6, 1
	v_lshlrev_b32_e32 v5, 5, v9
	v_ashrrev_i16_sdwa v1, v6, sext(v1) dst_sel:DWORD dst_unused:UNUSED_PAD src0_sel:DWORD src1_sel:BYTE_0
	v_and_b32_e32 v5, 32, v5
	v_bfe_i32 v11, v1, 0, 16
	v_add_lshl_u32 v1, v5, v11, 1
	v_lshl_add_u32 v130, v4, 10, v1
	v_lshl_add_u32 v132, v3, 10, v1
	v_bfe_i32 v1, v8, 27, 1
	v_lshrrev_b32_e32 v1, 22, v1
	v_add_u32_e32 v1, v0, v1
	v_and_b32_e32 v1, 0xfffffc00, v1
	v_sub_u32_e32 v0, v0, v1
	v_lshrrev_b32_e32 v1, 4, v0
	v_bitop3_b32 v1, v1, v0, 32 bitop3:0x6c
	v_ashrrev_i32_e32 v0, 31, v0
	s_add_u32 s1, s4, 0x600000
	v_lshrrev_b32_e32 v0, 26, v0
	s_addc_u32 s28, s5, 0
	v_add_u32_e32 v0, v1, v0
	s_add_u32 s29, s4, 0x21f00000
	v_ashrrev_i32_e32 v12, 6, v0
	v_ashrrev_i32_e32 v0, 31, v8
	s_mul_hi_i32 s6, s0, 0x2aaaaaab
	s_addc_u32 s30, s5, 0
	v_lshrrev_b32_e32 v0, 26, v0
	s_lshr_b32 s7, s6, 31
	s_ashr_i32 s6, s6, 5
	v_add_u32_e32 v0, v8, v0
	s_add_i32 s52, s6, s7
	v_ashrrev_i32_e32 v13, 6, v0
	s_mul_i32 s6, s52, 0xc0
	v_lshlrev_b32_e32 v0, 3, v13
	s_sub_i32 s6, s0, s6
	s_ashr_i32 s12, s10, 6
	v_and_b32_e32 v0, -16, v0
	s_and_b32 s53, s6, 3
	s_ashr_i32 s11, s10, 8
	s_lshl_b32 s31, s12, 10
	v_add_u32_e32 v0, v12, v0
	s_ashr_i32 s18, s6, 2
	s_lshl_b32 s6, s53, 18
	v_and_b32_e32 v2, 3, v12
	v_lshrrev_b32_e32 v3, 2, v0
	v_lshlrev_b32_e32 v4, 1, v0
	s_add_u32 s20, s1, s6
	v_and_or_b32 v2, v0, s2, v2
	v_and_b32_e32 v3, 4, v3
	v_and_b32_e32 v4, 24, v4
	s_addc_u32 s21, s28, 0
	s_ashr_i32 s19, s18, 31
	v_or3_b32 v2, v2, v3, v4
	v_mul_i32_i24_e32 v4, 64, v12
	s_lshl_b64 s[6:7], s[18:19], 18
	v_sub_u32_e32 v1, v1, v4
	s_add_u32 s6, s29, s6
	v_lshlrev_b32_e32 v3, 5, v13
	v_ashrrev_i16_sdwa v1, v6, sext(v1) dst_sel:DWORD dst_unused:UNUSED_PAD src0_sel:DWORD src1_sel:BYTE_0
	s_mul_i32 s9, s52, 0xc00000
	s_addc_u32 s7, s30, s7
	v_and_b32_e32 v3, 32, v3
	v_bfe_i32 v14, v1, 0, 16
	s_mul_hi_i32 s8, s52, 0xc00000
	s_add_u32 s22, s6, s9
	v_add_lshl_u32 v1, v3, v14, 1
	s_addc_u32 s23, s7, s8
	s_add_i32 s38, s31, 0
	v_lshl_add_u32 v134, v2, 10, v1
	s_add_i32 m0, s38, 0x10000
	v_lshl_add_u32 v136, v0, 10, v1
	global_load_lds_dwordx4 v134, s[22:23]
	s_add_i32 m0, s38, 0x12000
	s_add_u32 s6, s22, 0x20000
	global_load_lds_dwordx4 v130, s[22:23]
	s_addc_u32 s7, s23, 0
	s_add_i32 m0, s38, 0x14000
	s_add_i32 s39, s38, 0x2000
	global_load_lds_dwordx4 v134, s[6:7]
	s_add_i32 m0, s38, 0x16000
	v_mov_b32_e32 v135, v97
	global_load_lds_dwordx4 v130, s[6:7]
	s_mov_b32 m0, s38
	s_add_u32 s6, s20, 0x20000
	global_load_lds_dwordx4 v136, s[20:21]
	s_mov_b32 m0, s39
	s_addc_u32 s7, s21, 0
	s_add_i32 s40, s38, 0x4000
	global_load_lds_dwordx4 v132, s[20:21]
	s_mov_b32 m0, s40
	s_add_i32 s41, s38, 0x6000
	global_load_lds_dwordx4 v136, s[6:7]
	s_mov_b32 m0, s41
	v_mov_b32_e32 v131, v97
	global_load_lds_dwordx4 v132, s[6:7]
	v_mov_b32_e32 v137, v97
	v_mov_b32_e32 v133, v97
	s_cmp_eq_u32 s11, 1
	v_mov_b32_e32 v250, 1
	v_lshl_add_u64 v[6:7], s[22:23], 0, v[134:135]
	v_lshl_add_u64 v[4:5], s[22:23], 0, v[130:131]
	v_lshl_add_u64 v[0:1], s[20:21], 0, v[136:137]
	s_cselect_b64 s[6:7], -1, 0
	s_cmp_lg_u32 s11, 1
	v_lshl_add_u64 v[2:3], s[20:21], 0, v[132:133]
	s_cbranch_scc1 .LBB0_431
	s_barrier
